# v006 plus a static priority raise around the QK MFMA blocks of the attention-B loops
# speedup vs baseline: 1.0018x; 1.0008x over previous
.LBB0_1479:
	s_and_b32 s27, s43, 0xc000
	s_add_i32 s27, s27, 0
	v_add_u32_e32 v97, s27, v151
	v_add_u32_e32 v110, s27, v152
	ds_read_b128 v[166:169], v97 offset:36864
	ds_read_b128 v[170:173], v97 offset:40960
	ds_read_b128 v[174:177], v97 offset:45056
	ds_read_b128 v[178:181], v97 offset:49152
	ds_read_b128 v[182:185], v110 offset:36864
	ds_read_b128 v[186:189], v110 offset:40960
	ds_read_b128 v[190:193], v110 offset:45056
	ds_read_b128 v[194:197], v110 offset:49152
	s_mul_i32 s34, s46, 0x3000
	s_add_i32 s34, s34, 0
	v_add_u32_e32 v88, s34, v131
	v_add_u32_e32 v89, s34, v148
	v_add_u32_e32 v90, s34, v149
	v_add_u32_e32 v91, s34, v150
	ds_read_b128 v[198:201], v88
	ds_read_b128 v[202:205], v88 offset:4096
	ds_read_b128 v[234:237], v89
	ds_read_b128 v[238:241], v89 offset:4096
	ds_read_b128 v[242:245], v90
	ds_read_b128 v[246:249], v90 offset:4096
	ds_read_b128 v[250:253], v91
	ds_read_b128 v[214:217], v91 offset:4096
	v_add_u32_e32 v92, s27, v153
	v_add_u32_e32 v93, s27, v154
	s_setprio 1
	s_waitcnt lgkmcnt(8)
	v_mfma_f32_32x32x16_bf16 v[48:63], v[166:169], v[80:83], v[48:63]
	v_exp_f32_e32 v97, v64
	v_exp_f32_e32 v98, v65
	v_mfma_f32_32x32x16_bf16 v[32:47], v[170:173], v[80:83], v[32:47]
	v_exp_f32_e32 v99, v66
	v_exp_f32_e32 v100, v67
	v_cvt_pk_bf16_f32 v206, v97, v98
	v_mfma_f32_32x32x16_bf16 v[16:31], v[174:177], v[80:83], v[16:31]
	v_exp_f32_e32 v101, v68
	v_exp_f32_e32 v102, v69
	v_cvt_pk_bf16_f32 v207, v99, v100
	v_mfma_f32_32x32x16_bf16 v[0:15], v[178:181], v[80:83], v[0:15]
	v_exp_f32_e32 v103, v70
	v_exp_f32_e32 v104, v71
	v_cvt_pk_bf16_f32 v208, v101, v102
	v_mfma_f32_32x32x16_bf16 v[48:63], v[182:185], v[84:87], v[48:63]
	v_exp_f32_e32 v105, v72
	v_exp_f32_e32 v106, v73
	v_cvt_pk_bf16_f32 v209, v103, v104
	v_mfma_f32_32x32x16_bf16 v[32:47], v[186:189], v[84:87], v[32:47]
	v_exp_f32_e32 v107, v74
	v_exp_f32_e32 v108, v75
	v_cvt_pk_bf16_f32 v210, v105, v106
	v_mfma_f32_32x32x16_bf16 v[16:31], v[190:193], v[84:87], v[16:31]
	v_exp_f32_e32 v109, v76
	v_exp_f32_e32 v110, v77
	v_cvt_pk_bf16_f32 v211, v107, v108
	v_mfma_f32_32x32x16_bf16 v[0:15], v[194:197], v[84:87], v[0:15]
	v_exp_f32_e32 v111, v78
	v_exp_f32_e32 v137, v79
	v_cvt_pk_bf16_f32 v212, v109, v110
	s_setprio 0
	ds_read_b128 v[166:169], v92 offset:36864
	ds_read_b128 v[170:173], v92 offset:40960
	ds_read_b128 v[174:177], v92 offset:45056
	ds_read_b128 v[178:181], v92 offset:49152
	ds_read_b128 v[182:185], v93 offset:36864
	ds_read_b128 v[186:189], v93 offset:40960
	ds_read_b128 v[190:193], v93 offset:45056
	ds_read_b128 v[194:197], v93 offset:49152
	v_cvt_pk_bf16_f32 v213, v111, v137
	s_waitcnt lgkmcnt(8)
	s_setprio 1
	v_mfma_f32_32x32x16_bf16 v[80:95], v[198:201], v[114:117], 0
	v_add_f32_e32 v97, v98, v97
	v_add_f32_e32 v97, v99, v97
	v_mfma_f32_32x32x16_bf16 v[64:79], v[202:205], v[114:117], 0
	v_add_f32_e32 v97, v100, v97
	v_add_f32_e32 v97, v101, v97
	v_mfma_f32_32x32x16_bf16 v[80:95], v[234:237], v[118:121], v[80:95]
	v_add_f32_e32 v97, v102, v97
	v_add_f32_e32 v97, v103, v97
	v_mfma_f32_32x32x16_bf16 v[64:79], v[238:241], v[118:121], v[64:79]
	v_add_f32_e32 v97, v104, v97
	v_add_f32_e32 v97, v105, v97
	v_mfma_f32_32x32x16_bf16 v[80:95], v[242:245], v[122:125], v[80:95]
	v_add_f32_e32 v97, v106, v97
	v_add_f32_e32 v97, v107, v97
	v_mfma_f32_32x32x16_bf16 v[64:79], v[246:249], v[122:125], v[64:79]
	v_add_f32_e32 v97, v108, v97
	v_add_f32_e32 v97, v109, v97
	v_mfma_f32_32x32x16_bf16 v[80:95], v[250:253], v[126:129], v[80:95]
	v_add_f32_e32 v97, v110, v97
	v_add_f32_e32 v97, v111, v97
	v_mfma_f32_32x32x16_bf16 v[64:79], v[214:217], v[126:129], v[64:79]
	s_setprio 0
	v_add_f32_e32 v97, v137, v97
	v_add_f32_e32 v96, v96, v97
	s_waitcnt lgkmcnt(0)
	s_setprio 1
	v_mfma_f32_32x32x16_bf16 v[48:63], v[166:169], v[206:209], v[48:63]
	v_mfma_f32_32x32x16_bf16 v[32:47], v[170:173], v[206:209], v[32:47]
	v_mfma_f32_32x32x16_bf16 v[16:31], v[174:177], v[206:209], v[16:31]
	v_mfma_f32_32x32x16_bf16 v[0:15], v[178:181], v[206:209], v[0:15]
	v_cmp_neq_f32_e32 vcc, 0, v164
	s_nop 4
	s_cbranch_vccz .Lb2_nosub
	s_nop 8
	v_sub_f32_e32 v95, v95, v164
	v_sub_f32_e32 v94, v94, v164
	v_sub_f32_e32 v93, v93, v164
	v_sub_f32_e32 v92, v92, v164
	v_sub_f32_e32 v91, v91, v164
	v_sub_f32_e32 v90, v90, v164
	v_sub_f32_e32 v89, v89, v164
	v_sub_f32_e32 v88, v88, v164
	v_sub_f32_e32 v87, v87, v164
	v_sub_f32_e32 v86, v86, v164
	v_sub_f32_e32 v85, v85, v164
	v_sub_f32_e32 v84, v84, v164
	v_sub_f32_e32 v83, v83, v164
	v_sub_f32_e32 v82, v82, v164
	v_sub_f32_e32 v81, v81, v164
	v_sub_f32_e32 v80, v80, v164
	v_sub_f32_e32 v79, v79, v164
	v_sub_f32_e32 v78, v78, v164
	v_sub_f32_e32 v77, v77, v164
	v_sub_f32_e32 v76, v76, v164
	v_sub_f32_e32 v75, v75, v164
	v_sub_f32_e32 v74, v74, v164
	v_sub_f32_e32 v73, v73, v164
	v_sub_f32_e32 v72, v72, v164
	v_sub_f32_e32 v71, v71, v164
	v_sub_f32_e32 v70, v70, v164
	v_sub_f32_e32 v69, v69, v164
	v_sub_f32_e32 v68, v68, v164
	v_sub_f32_e32 v67, v67, v164
	v_sub_f32_e32 v66, v66, v164
	v_sub_f32_e32 v65, v65, v164
	v_sub_f32_e32 v64, v64, v164

.LBB0_1501:
	s_mul_i32 s13, s35, 0x3000
	s_add_i32 s13, s13, 0
	v_add_u32_e32 v106, s13, v131
	v_add_u32_e32 v107, s13, v148
	v_add_u32_e32 v108, s13, v149
	v_add_u32_e32 v109, s13, v150
	ds_read_b128 v[198:201], v106
	ds_read_b128 v[202:205], v106 offset:4096
	ds_read_b128 v[234:237], v107
	ds_read_b128 v[238:241], v107 offset:4096
	ds_read_b128 v[242:245], v108
	ds_read_b128 v[246:249], v108 offset:4096
	ds_read_b128 v[250:253], v109
	ds_read_b128 v[214:217], v109 offset:4096
	s_and_b32 s13, s29, 0xc000
	s_add_i32 s13, s13, 0
	v_add_u32_e32 v110, s13, v151
	v_add_u32_e32 v111, s13, v152
	ds_read_b128 v[166:169], v110 offset:36864
	ds_read_b128 v[170:173], v110 offset:40960
	ds_read_b128 v[174:177], v110 offset:45056
	ds_read_b128 v[178:181], v110 offset:49152
	ds_read_b128 v[182:185], v111 offset:36864
	ds_read_b128 v[186:189], v111 offset:40960
	ds_read_b128 v[190:193], v111 offset:45056
	ds_read_b128 v[194:197], v111 offset:49152
	v_add_u32_e32 v142, s13, v153
	v_add_u32_e32 v143, s13, v154
	s_waitcnt lgkmcnt(8)
	s_setprio 1
	v_mfma_f32_32x32x16_bf16 v[80:95], v[198:201], v[114:117], 0
	v_mfma_f32_32x32x16_bf16 v[64:79], v[202:205], v[114:117], 0
	v_mfma_f32_32x32x16_bf16 v[80:95], v[234:237], v[118:121], v[80:95]
	v_mfma_f32_32x32x16_bf16 v[64:79], v[238:241], v[118:121], v[64:79]
	v_mfma_f32_32x32x16_bf16 v[80:95], v[242:245], v[122:125], v[80:95]
	v_mfma_f32_32x32x16_bf16 v[64:79], v[246:249], v[122:125], v[64:79]
	v_mfma_f32_32x32x16_bf16 v[80:95], v[250:253], v[126:129], v[80:95]
	v_mfma_f32_32x32x16_bf16 v[64:79], v[214:217], v[126:129], v[64:79]
	s_setprio 0
	ds_read_b128 v[198:201], v142 offset:36864
	ds_read_b128 v[202:205], v142 offset:40960
	ds_read_b128 v[234:237], v142 offset:45056
	ds_read_b128 v[238:241], v142 offset:49152
	ds_read_b128 v[242:245], v143 offset:36864
	ds_read_b128 v[246:249], v143 offset:40960
	ds_read_b128 v[250:253], v143 offset:45056
	ds_read_b128 v[214:217], v143 offset:49152
	v_cmp_neq_f32_e32 vcc, 0, v164
	s_cbranch_vccz .La2_nosub
	s_nop 8
	v_sub_f32_e32 v95, v95, v164
	v_sub_f32_e32 v94, v94, v164
	v_sub_f32_e32 v93, v93, v164
	v_sub_f32_e32 v92, v92, v164
	v_sub_f32_e32 v91, v91, v164
	v_sub_f32_e32 v90, v90, v164
	v_sub_f32_e32 v89, v89, v164
	v_sub_f32_e32 v88, v88, v164
	v_sub_f32_e32 v87, v87, v164
	v_sub_f32_e32 v86, v86, v164
	v_sub_f32_e32 v85, v85, v164
	v_sub_f32_e32 v84, v84, v164
	v_sub_f32_e32 v83, v83, v164
	v_sub_f32_e32 v82, v82, v164
	v_sub_f32_e32 v81, v81, v164
	v_sub_f32_e32 v80, v80, v164
	v_sub_f32_e32 v79, v79, v164
	v_sub_f32_e32 v78, v78, v164
	v_sub_f32_e32 v77, v77, v164
	v_sub_f32_e32 v76, v76, v164
	v_sub_f32_e32 v75, v75, v164
	v_sub_f32_e32 v74, v74, v164
	v_sub_f32_e32 v73, v73, v164
	v_sub_f32_e32 v72, v72, v164
	v_sub_f32_e32 v71, v71, v164
	v_sub_f32_e32 v70, v70, v164
	v_sub_f32_e32 v69, v69, v164
	v_sub_f32_e32 v68, v68, v164
	v_sub_f32_e32 v67, v67, v164
	v_sub_f32_e32 v66, v66, v164
	v_sub_f32_e32 v65, v65, v164
	v_sub_f32_e32 v64, v64, v164
